# SCAN: logical wave ids of waves 4-7 relabelled (4<->7, 5<->6) so each SIMD pair carries equal triangular work
# speedup vs baseline: 1.0103x; 1.0047x over previous
; #define LAS __attribute__((address_space(3)))
; __device__ __forceinline__ void scan_prompt_unit(const Ctx& c, int b, int h) {
;     LAS unsigned char* lds = c.lds;
;     const int tid = c.tid, lane = c.lane, w = c.wave, q = lane >> 4, c16 = lane & 15, g = h >> 3;
;     bf16_t* XBC = (bf16_t*)(c.ws + OFF_XBC);
;     const float* DTS = (const float*)(c.ws + OFF_DTS); const float* ACS = (const float*)(c.ws + OFF_ACS);
;     const float Dh = GIN(c, 19)[h];
;     LAS float* acsL = (LAS float*)(lds + SC_F); LAS float* dtL = acsL + 128;
;     f32x4 hacc[4];
; #pragma unroll
;     for (int pt = 0; pt < 4; ++pt) hacc[pt] = (f32x4){0.f, 0.f, 0.f, 0.f};
;     for (int i = tid; i < 64 * SROW / 4; i += 512) ((LAS unsigned*)(lds + SC_H))[i] = 0u;
;     u32x4 pc[4], pb[4], px[2]; float pdt[4], pac[4], pa_last, pa_mine = 0.f, pd_mine = 0.f;
;     const int prow = tid >> 4, pcc = tid & 15, xrow = tid >> 3, xcc = tid & 7;
.LBB0_138:
	s_cmp_lt_u32 s92, 4
	s_cbranch_scc1 .Lscan_perm1
	s_sub_i32 s92, 11, s92
.Lscan_perm1:
	s_lshl_b32 s77, s92, 6
	v_lshl_or_b32 v164, s92, 6, v162
	s_add_i32 s32, s92, s93
	v_writelane_b32 v254, s32, 16
	v_writelane_b32 v254, s6, 22
	v_readlane_b32 s2, v251, 37
	v_readlane_b32 s3, v251, 38
	v_writelane_b32 v254, s7, 23
	v_writelane_b32 v254, s77, 24
	v_writelane_b32 v254, s78, 25
	s_andn2_b64 vcc, exec, s[2:3]
	s_nop 0
	v_writelane_b32 v254, s79, 26
	v_writelane_b32 v254, s96, 27
	v_writelane_b32 v254, s93, 28
	v_writelane_b32 v254, s94, 29
	s_nop 1
	v_writelane_b32 v254, s95, 30
	s_cbranch_vccnz .LBB0_209
	s_add_u32 s2, s90, 0xc24000
	s_addc_u32 s3, s91, 0
	s_add_u32 s4, s90, 0x13488000
	v_writelane_b32 v254, s2, 31
	s_addc_u32 s5, s91, 0
	s_waitcnt vmcnt(0)
	v_and_b32_e32 v12, 15, v164
	v_writelane_b32 v254, s3, 32
	s_add_u32 s2, s90, 0x1044000
	s_addc_u32 s3, s91, 0
	v_writelane_b32 v254, s2, 33
	s_lshl_b32 s10, s92, 4
	v_or_b32_e32 v16, s10, v12
	v_writelane_b32 v254, s3, 34
	s_movk_i32 s2, 0x1100
	v_cmp_gt_i32_e64 s[2:3], s2, v164
	s_movk_i32 s7, 0x110
	v_mul_lo_u32 v6, v16, s7
	v_writelane_b32 v254, s2, 35
	v_add_u32_e32 v191, 0, v6
	v_bfe_u32 v6, v164, 2, 2
	v_writelane_b32 v254, s3, 36
	s_movk_i32 s2, 0x80
	v_lshrrev_b32_e32 v10, 1, v164
	v_lshlrev_b32_e32 v4, 4, v12
	v_cmp_gt_i32_e64 s[40:41], s2, v164
	v_readlane_b32 s2, v253, 39
	v_and_or_b32 v13, v10, 24, v6
	v_lshlrev_b32_e32 v6, 3, v162
	s_lshl_b32 s3, s92, 5
	s_waitcnt lgkmcnt(0)
	v_mov_b32_e32 v5, v2
	v_writelane_b32 v254, s4, 37
	v_add_u32_e32 v3, s2, v4
	v_readlane_b32 s6, v253, 40
	v_and_b32_e32 v6, 24, v6
	s_add_i32 s2, s2, s3
	v_writelane_b32 v254, s5, 38
	v_lshl_add_u64 v[144:145], s[4:5], 0, v[4:5]
	v_lshlrev_b32_e32 v14, 2, v164
	v_readlane_b32 s4, v253, 37
	v_add_u32_e32 v11, s2, v6
	v_add_u32_e32 v10, s6, v6
	v_and_b32_e32 v6, 48, v162
	v_add_u32_e32 v153, s4, v14
	v_add_u32_e32 v195, s4, v6
	v_readlane_b32 s4, v254, 24
	v_lshrrev_b32_e32 v7, 4, v162
	s_ashr_i32 s11, s4, 7
	s_movk_i32 s4, 0x90
	v_lshlrev_b32_e32 v17, 2, v7
	v_lshlrev_b32_e32 v196, 3, v7
	v_mul_lo_u32 v7, v16, s4
	v_add_u32_e32 v18, s6, v7
	v_or_b32_e32 v7, 3, v17
	v_and_b32_e32 v5, 7, v164
	v_cmp_gt_i32_e64 s[46:47], v7, v16
	v_or_b32_e32 v7, 17, v17
	v_ashrrev_i32_e32 v140, 4, v164
	v_lshlrev_b32_e32 v15, 4, v5
	v_mul_u32_u24_e32 v23, 0x110, v13
	v_mul_u32_u24_e32 v24, 0x90, v13
	v_or_b32_e32 v13, 2, v17
	v_cmp_gt_i32_e64 s[94:95], v7, v16
	v_or_b32_e32 v7, 19, v17
	v_ashrrev_i32_e32 v142, 3, v164
	v_lshlrev_b32_e32 v0, 3, v5
	v_readlane_b32 s5, v253, 38
	v_add_u32_e32 v5, s6, v15
	v_mul_lo_u32 v20, v140, s7
	v_cmp_gt_i32_e64 s[48:49], v13, v16
	v_or_b32_e32 v13, 16, v17
	v_cmp_gt_i32_e64 s[6:7], v7, v16
	v_add_u32_e32 v190, s5, v14
	v_lshl_add_u32 v193, v16, 2, s5
	v_add_u32_e32 v194, s5, v6
	v_mul_lo_u32 v21, v142, s4
	v_cmp_gt_i32_e64 s[4:5], v13, v16
	v_or_b32_e32 v13, 18, v17
	v_writelane_b32 v254, s6, 39
	v_or_b32_e32 v7, 33, v17
	s_add_i32 s12, 0, 0x1e000
	v_writelane_b32 v254, s7, 40
	v_cmp_gt_i32_e64 s[6:7], v13, v16
	v_or_b32_e32 v13, 32, v17
	s_or_b32 s2, s92, 1
	v_writelane_b32 v254, s6, 41
	s_add_i32 s3, s3, s12
	s_cmp_gt_i32 s92, -1
	v_writelane_b32 v254, s7, 42
	v_cmp_gt_i32_e64 s[6:7], v7, v16
	v_or_b32_e32 v7, 35, v17
	s_cselect_b64 s[24:25], -1, 0
	v_writelane_b32 v254, s6, 43
	s_cmp_gt_i32 s92, 0
	s_cselect_b64 s[26:27], -1, 0
	v_writelane_b32 v254, s7, 44
	v_cmp_gt_i32_e64 s[6:7], v13, v16
	v_or_b32_e32 v13, 34, v17
	s_cmp_gt_i32 s92, 1
	v_writelane_b32 v254, s6, 45
	s_cselect_b64 s[36:37], -1, 0
	s_cmp_gt_i32 s92, 2
	v_writelane_b32 v254, s7, 46
	v_cmp_gt_i32_e64 s[6:7], v7, v16
	v_or_b32_e32 v7, 49, v17
	s_cselect_b64 s[50:51], -1, 0
	v_writelane_b32 v254, s6, 47
	s_cmp_gt_i32 s92, 3
	s_cselect_b64 s[52:53], -1, 0
	v_writelane_b32 v254, s7, 48
	v_cmp_gt_i32_e64 s[6:7], v13, v16
	v_or_b32_e32 v13, 48, v17
	s_cmp_gt_i32 s92, 4
	v_writelane_b32 v254, s6, 49
	s_cselect_b64 s[54:55], -1, 0
	s_cmp_gt_i32 s92, 5
	v_writelane_b32 v254, s7, 50
	v_cmp_gt_i32_e64 s[6:7], v7, v16
	v_or_b32_e32 v7, 51, v17
	s_cselect_b64 s[56:57], -1, 0
	v_writelane_b32 v254, s6, 51
	s_cmp_gt_i32 s92, 6
	s_cselect_b64 s[58:59], -1, 0
	v_writelane_b32 v254, s7, 52
	v_cmp_gt_i32_e64 s[6:7], v13, v16
	v_or_b32_e32 v13, 50, v17
	s_cmp_gt_i32 s2, 1
; #define LAS __attribute__((address_space(3)))
; __device__ __forceinline__ unsigned cvt_pk_bf16(float lo, float hi) { f32x2 v = {lo, hi}; bf16x2_t b = __builtin_convertvector(v, bf16x2_t); return __builtin_bit_cast(unsigned, b); }
; __device__ __forceinline__ void scan_prompt_unit(const Ctx& c, int b, int h) {
;     ...
;                 if (st <= (w | 1)) {
;                     u32x2 pk; pk.x = 0u; pk.y = 0u;
;                     if (st <= w) {
;                         const f32x4 as = *(const LAS f32x4*)(acsL + 16 * st + 4 * q), ds = *(const LAS f32x4*)(dtL + 16 * st + 4 * q);
;                         float v[4];
; #pragma unroll
;                         for (int r = 0; r < 4; ++r) { const int s_ = 16 * st + 4 * q + r; const float e = __expf(acs_l - as[r]) * ds[r] * cb[st][r]; v[r] = (s_ <= l) ? e : 0.f; }
;                         pk.x = cvt_pk_bf16(v[0], v[1]); pk.y = cvt_pk_bf16(v[2], v[3]);
;                     }
;                     *(LAS u32x2*)(lds + SC_B + l * SROW + (16 * st + 4 * q) * 2) = pk;
;                 }
;             }
;         }
;         f32x4 yd[4];
; #pragma unroll
;         for (int pt = 0; pt < 4; ++pt) yd[pt] = (f32x4){0.f, 0.f, 0.f, 0.f};
; #pragma unroll
;         for (int ks = 0; ks < 4; ++ks) {
;             if (ks <= (w >> 1)) {
;                 const bf16x8 wf = *(const LAS bf16x8*)(lds + SC_B + (16 * w + c16) * SROW + (32 * ks + 8 * q) * 2);
	v_writelane_b32 v254, s6, 53
	s_cselect_b64 s[60:61], -1, 0
	s_cmp_gt_i32 s2, 2
	v_writelane_b32 v254, s7, 54
	v_cmp_gt_i32_e64 s[6:7], v7, v16
	v_or_b32_e32 v7, 0x41, v17
	s_cselect_b64 s[62:63], -1, 0
	v_writelane_b32 v254, s6, 55
	s_cmp_gt_i32 s2, 3
	s_cselect_b64 s[64:65], -1, 0
	v_writelane_b32 v254, s7, 56
	v_cmp_gt_i32_e64 s[6:7], v13, v16
	v_or_b32_e32 v13, 64, v17
	s_cmp_gt_i32 s2, 4
	v_writelane_b32 v254, s6, 57
	s_cselect_b64 s[66:67], -1, 0
	s_cmp_gt_i32 s2, 5
	v_writelane_b32 v254, s7, 58
	v_cmp_gt_i32_e64 s[6:7], v7, v16
	v_or_b32_e32 v7, 0x43, v17
	v_add_u32_e32 v19, s3, v196
	v_writelane_b32 v254, s6, 59
	s_cselect_b64 s[68:69], -1, 0
	s_cmp_gt_i32 s2, 6
	v_writelane_b32 v254, s7, 60
	v_cmp_gt_i32_e64 s[6:7], v13, v16
	v_or_b32_e32 v13, 0x42, v17
	s_cselect_b64 s[70:71], -1, 0
	v_writelane_b32 v254, s6, 61
	s_cmp_gt_i32 s11, -1
	s_cselect_b64 s[72:73], -1, 0
	v_writelane_b32 v254, s7, 62
	v_cmp_gt_i32_e64 s[6:7], v7, v16
	v_or_b32_e32 v7, 0x51, v17
	s_cmp_gt_i32 s11, 0
	v_writelane_b32 v254, s6, 63
	s_cselect_b64 s[74:75], -1, 0
	s_cmp_gt_i32 s11, 1
	v_writelane_b32 v250, s7, 0
	v_cmp_gt_i32_e64 s[6:7], v13, v16
	v_or_b32_e32 v13, 0x50, v17
	s_cselect_b64 s[76:77], -1, 0
	v_writelane_b32 v250, s6, 1
	s_cmp_gt_i32 s11, 2
	s_cselect_b64 s[78:79], -1, 0
	v_writelane_b32 v250, s7, 2
	v_cmp_gt_i32_e64 s[6:7], v7, v16
	v_or_b32_e32 v7, 0x53, v17
	s_ashr_i32 s11, s10, 31
	v_writelane_b32 v250, s6, 3
	s_lshl_b64 s[10:11], s[10:11], 2
	v_mul_u32_u24_e32 v22, 0x110, v12
	v_writelane_b32 v250, s7, 4
	v_cmp_gt_i32_e64 s[6:7], v13, v16
	v_or_b32_e32 v13, 0x52, v17
	v_lshlrev_b32_e32 v12, 9, v12
	v_writelane_b32 v250, s6, 5
	v_and_b32_e32 v192, 48, v164
	v_add_u32_e32 v1, 0, v4
	v_writelane_b32 v250, s7, 6
	v_cmp_gt_i32_e64 s[6:7], v7, v16
	v_or_b32_e32 v7, 0x61, v17
	v_ashrrev_i32_e32 v141, 31, v140
	v_writelane_b32 v250, s6, 7
	v_add_u32_e32 v8, 0, v192
	v_add_u32_e32 v9, s12, v192
	v_writelane_b32 v250, s7, 8
	v_cmp_gt_i32_e64 s[6:7], v13, v16
	v_or_b32_e32 v13, 0x60, v17
	v_mov_b32_e32 v165, v2
	v_writelane_b32 v250, s6, 9
	v_ashrrev_i32_e32 v143, 31, v142
	v_cmp_gt_i32_e64 s[42:43], v17, v16
	v_writelane_b32 v250, s7, 10
	v_cmp_gt_i32_e64 s[6:7], v7, v16
	v_or_b32_e32 v7, 0x63, v17
	v_cmp_lt_i32_e64 s[44:45], v17, v16
	v_writelane_b32 v250, s6, 11
	v_mov_b64_e32 v[146:147], v[164:165]
	v_ashrrev_i32_e32 v165, 31, v164
	v_writelane_b32 v250, s7, 12
	v_cmp_gt_i32_e64 s[6:7], v13, v16
	v_or_b32_e32 v13, 0x62, v17
	v_add_u32_e32 v197, 0xfffffe00, v164
	v_writelane_b32 v250, s6, 13
	v_add_u32_e32 v198, s12, v14
	v_lshlrev_b64 v[170:171], 7, v[140:141]
	v_writelane_b32 v250, s7, 14
	v_cmp_gt_i32_e64 s[6:7], v7, v16
	v_or_b32_e32 v7, 0x71, v17
	v_cmp_gt_i32_e64 s[2:3], v7, v16
	v_writelane_b32 v250, s6, 15
	v_or_b32_e32 v7, 0x73, v17
	v_lshlrev_b32_e32 v176, 1, v0
	v_writelane_b32 v250, s7, 16
	v_cmp_gt_i32_e64 s[6:7], v13, v16
	v_or_b32_e32 v13, 0x70, v17
	v_add_u32_e32 v199, v1, v20
	v_writelane_b32 v250, s6, 17
	v_add_u32_e32 v200, v3, v20
	v_add_u32_e32 v201, v5, v21
	v_writelane_b32 v250, s7, 18
	v_writelane_b32 v250, s2, 19
	v_add_u32_e32 v202, v9, v22
	v_add_u32_e32 v203, v11, v23
	v_writelane_b32 v250, s3, 20
	v_cmp_gt_i32_e64 s[2:3], v13, v16
	v_or_b32_e32 v13, 0x72, v17
	v_cmp_gt_i32_e64 s[8:9], v13, v16
	v_writelane_b32 v250, s2, 21
	v_mov_b32_e32 v13, v2
	v_add_u32_e32 v204, v18, v196
	v_writelane_b32 v250, s3, 22
	v_cmp_gt_i32_e64 s[2:3], v7, v16
	v_mov_b32_e32 v7, v2
	v_add_u32_e32 v205, v19, v22
	v_writelane_b32 v250, s2, 23
	v_add_u32_e32 v206, v8, v22
	v_add_u32_e32 v207, v10, v24
	v_writelane_b32 v250, s3, 24
	v_readlane_b32 s2, v254, 8
	v_readlane_b32 s3, v254, 9
	s_add_u32 s10, s2, s10
	s_addc_u32 s11, s3, s11
	v_lshl_add_u64 v[6:7], s[10:11], 0, v[6:7]
	v_lshl_add_u64 v[6:7], v[6:7], 0, v[12:13]
	s_mov_b64 s[10:11], 0x8400000
	s_movk_i32 s2, 0x1800
	v_lshl_add_u64 v[166:167], v[6:7], 0, s[10:11]
	v_mad_i64_i32 v[172:173], s[10:11], v140, s2, 0
	v_mad_i64_i32 v[168:169], s[10:11], v142, s2, 0
	v_or_b32_e32 v172, v172, v4
	v_mad_i64_i32 v[6:7], s[10:11], v16, s2, 0
	v_lshrrev_b32_e32 v4, 1, v192
	v_or_b32_e32 v6, v6, v4
	s_mov_b64 s[10:11], 0x13488040
	v_or_b32_e32 v168, v168, v15
	v_lshl_add_u64 v[174:175], v[6:7], 0, s[10:11]
	s_mov_b32 s96, s33
	s_mov_b32 s2, s33
	s_branch .LBB0_141
